# P5 EpiResLN: residual-row load batches issued 2 deep into alternating register sets behind counted vmcnt(4) (was 8 serial load+wait batches per tile); on top of P1 LDS ring prefetch
# speedup vs baseline: 1.0170x; 1.0027x over previous
;     __device__ __forceinline__ void operator()(f32x4 (&acc)[2][2][4][2], const Unit& u, int wr, int wc, int fr, int fq, LAS unsigned char* lds) const {
;     ...
;         {
;             const float* gr = gatef + (u.pm >> 3) * DM + col0;
;             f32x4 gv[2][2];
; #pragma unroll
;             for (int bj = 0; bj < 2; ++bj) { gv[bj][0] = *(const f32x4*)(gr + bj * HALF); gv[bj][1] = *(const f32x4*)(gr + bj * HALF + 4); }
; #pragma unroll
;             for (int ai = 0; ai < 2; ++ai)
; #pragma unroll
;                 for (int m = 0; m < 4; ++m) { int rr_ = row0 + ai * HALF + m * 16; asm volatile("" : "+v"(rr_)); const float* xr = xp + (size_t)rr_ * DM + col0;
;                     float sq = 0.f;
; #pragma unroll
;                     for (int bj = 0; bj < 2; ++bj) { const f32x4 v0 = *(const f32x4*)(xr + bj * HALF) + gv[bj][0] * acc[ai][bj][m][0], v1 = *(const f32x4*)(xr + bj * HALF + 4) + gv[bj][1] * acc[ai][bj][m][1];
;                         acc[ai][bj][m][0] = v0; acc[ai][bj][m][1] = v1;
;                         sq += ((v0[0] * v0[0] + v0[1] * v0[1]) + (v0[2] * v0[2] + v0[3] * v0[3])) + ((v1[0] * v1[0] + v1[1] * v1[1]) + (v1[2] * v1[2] + v1[3] * v1[3])); }
;                     sq += __shfl_xor(sq, 16); sq += __shfl_xor(sq, 32);
;                     if (fq == 0) P[(ai * HALF + wr * 64 + m * 16 + fr) * 4 + wc] = sq; }
.LBB0_1217:
	s_lshl_b32 s4, s73, 8
	s_add_i32 s16, s4, s62
	s_lshl_b32 s4, s73, 7
	s_and_b32 s4, s4, 0xfffffc00
	v_mov_b32_e32 v160, v180
	s_ashr_i32 s5, s4, 31
	s_lshl_b64 s[4:5], s[4:5], 2
	v_bfe_u32 v190, v160, 4, 2
	v_and_b32_e32 v159, 15, v160
	v_lshl_or_b32 v116, v190, 3, s68
	s_add_u32 s4, s22, s4
	v_or_b32_e32 v158, s16, v159
	s_addc_u32 s5, s23, s5
	v_lshlrev_b32_e32 v152, 2, v116
	v_mov_b32_e32 v162, v158
	global_load_dwordx4 v[128:131], v152, s[4:5] offset:16
	global_load_dwordx4 v[132:135], v152, s[4:5]
	global_load_dwordx4 v[116:119], v152, s[4:5] offset:528
	global_load_dwordx4 v[124:127], v152, s[4:5] offset:512
	v_xor_b32_e32 v161, 16, v176
	v_ashrrev_i32_e32 v163, 31, v162
	v_lshlrev_b64 v[162:163], 12, v[162:163]
	v_lshl_add_u64 v[162:163], s[36:37], 0, v[162:163]
	v_lshl_add_u64 v[174:175], v[162:163], 0, v[152:153]
	global_load_dwordx4 v[218:221], v[174:175], off
	global_load_dwordx4 v[222:225], v[174:175], off offset:16
	global_load_dwordx4 v[226:229], v[174:175], off offset:512
	global_load_dwordx4 v[230:233], v[174:175], off offset:528
	v_add_u32_e32 v250, 16, v158
	v_ashrrev_i32_e32 v251, 31, v250
	v_lshlrev_b64 v[250:251], 12, v[250:251]
	v_lshl_add_u64 v[250:251], s[36:37], 0, v[250:251]
	v_lshl_add_u64 v[250:251], v[250:251], 0, v[152:153]
	global_load_dwordx4 v[234:237], v[250:251], off
	global_load_dwordx4 v[238:241], v[250:251], off offset:16
	global_load_dwordx4 v[242:245], v[250:251], off offset:512
	global_load_dwordx4 v[246:249], v[250:251], off offset:528
	v_and_b32_e32 v174, 64, v176
	v_add_u32_e32 v179, 64, v174
	v_cmp_lt_i32_e32 vcc, v161, v179
	s_waitcnt vmcnt(4)
	v_pk_fma_f32 v[142:143], v[142:143], v[134:135], v[220:221]
	v_cndmask_b32_e32 v161, v176, v161, vcc
	v_pk_fma_f32 v[162:163], v[140:141], v[132:133], v[218:219]
	v_pk_fma_f32 v[138:139], v[138:139], v[130:131], v[224:225]
	v_pk_fma_f32 v[140:141], v[136:137], v[128:129], v[222:223]
	v_pk_fma_f32 v[122:123], v[122:123], v[126:127], v[228:229]
	v_pk_fma_f32 v[136:137], v[120:121], v[124:125], v[226:227]
	v_pk_fma_f32 v[114:115], v[114:115], v[118:119], v[232:233]
	v_pk_fma_f32 v[120:121], v[112:113], v[116:117], v[230:231]
	v_lshlrev_b32_e32 v177, 2, v161
	v_mul_f32_e32 v112, v163, v163
	v_mul_f32_e32 v113, v143, v143
	v_mul_f32_e32 v161, v141, v141
	v_mul_f32_e32 v164, v139, v139
	v_mul_f32_e32 v165, v137, v137
	v_mul_f32_e32 v166, v123, v123
	v_mul_f32_e32 v167, v121, v121
	v_mul_f32_e32 v168, v115, v115
	v_fmac_f32_e32 v112, v162, v162
	v_fmac_f32_e32 v113, v142, v142
	v_fmac_f32_e32 v161, v140, v140
	v_fmac_f32_e32 v164, v138, v138
	v_fmac_f32_e32 v165, v136, v136
	v_fmac_f32_e32 v166, v122, v122
	v_fmac_f32_e32 v167, v120, v120
	v_fmac_f32_e32 v168, v114, v114
	v_add_f32_e32 v112, v112, v113
	v_add_f32_e32 v113, v161, v164
	v_add_f32_e32 v161, v165, v166
	v_add_f32_e32 v164, v167, v168
	v_add_f32_e32 v112, v112, v113
	v_add_f32_e32 v113, v161, v164
	v_add_f32_e32 v112, v112, v113
	ds_bpermute_b32 v113, v177, v112
	v_xor_b32_e32 v161, 32, v176
	v_cmp_lt_i32_e32 vcc, v161, v179
	s_waitcnt lgkmcnt(0)
	v_add_f32_e32 v112, v112, v113
	v_cndmask_b32_e32 v161, v176, v161, vcc
	v_lshlrev_b32_e32 v178, 2, v161
	ds_bpermute_b32 v161, v178, v112
	v_or_b32_e32 v113, s62, v159
	v_cmp_eq_u32_e32 vcc, 0, v190
	v_lshl_add_u32 v113, v113, 4, s66
	s_and_saveexec_b64 s[4:5], vcc
	s_cbranch_execz .LBB0_1219
	s_waitcnt lgkmcnt(0)
	v_add_f32_e32 v112, v112, v161
	ds_write_b32 v113, v112
.LBB0_1219:
	s_or_b64 exec, exec, s[4:5]
	v_or_b32_e32 v112, 16, v158
	v_mov_b32_e32 v164, v112
	s_nop 0
	v_ashrrev_i32_e32 v165, 31, v164
	v_lshlrev_b64 v[164:165], 12, v[164:165]
	v_lshl_add_u64 v[164:165], s[36:37], 0, v[164:165]
	v_lshl_add_u64 v[186:187], v[164:165], 0, v[152:153]
	v_add_u32_e32 v250, 32, v158
	v_ashrrev_i32_e32 v251, 31, v250
	v_lshlrev_b64 v[250:251], 12, v[250:251]
	v_lshl_add_u64 v[250:251], s[36:37], 0, v[250:251]
	v_lshl_add_u64 v[250:251], v[250:251], 0, v[152:153]
	global_load_dwordx4 v[218:221], v[250:251], off
	global_load_dwordx4 v[222:225], v[250:251], off offset:16
	global_load_dwordx4 v[226:229], v[250:251], off offset:512
	global_load_dwordx4 v[230:233], v[250:251], off offset:528
	s_nop 0
	s_waitcnt vmcnt(4)
	v_pk_fma_f32 v[110:111], v[110:111], v[134:135], v[236:237]
	v_pk_fma_f32 v[164:165], v[108:109], v[132:133], v[234:235]
	v_pk_fma_f32 v[106:107], v[106:107], v[130:131], v[240:241]
	v_pk_fma_f32 v[108:109], v[104:105], v[128:129], v[238:239]
	v_pk_fma_f32 v[102:103], v[102:103], v[126:127], v[244:245]
	v_pk_fma_f32 v[104:105], v[100:101], v[124:125], v[242:243]
	v_pk_fma_f32 v[98:99], v[98:99], v[118:119], v[248:249]
	v_pk_fma_f32 v[100:101], v[96:97], v[116:117], v[246:247]
	v_mul_f32_e32 v96, v165, v165
	v_mul_f32_e32 v97, v111, v111
	s_waitcnt lgkmcnt(0)
	v_mul_f32_e32 v161, v109, v109
	v_mul_f32_e32 v166, v107, v107
	v_mul_f32_e32 v167, v105, v105
	v_mul_f32_e32 v168, v103, v103
	v_mul_f32_e32 v169, v101, v101
	v_mul_f32_e32 v170, v99, v99
	v_fmac_f32_e32 v96, v164, v164
	v_fmac_f32_e32 v97, v110, v110
	v_fmac_f32_e32 v161, v108, v108
	v_fmac_f32_e32 v166, v106, v106
	v_fmac_f32_e32 v167, v104, v104
	v_fmac_f32_e32 v168, v102, v102
	v_fmac_f32_e32 v169, v100, v100
	v_fmac_f32_e32 v170, v98, v98
	v_add_f32_e32 v96, v96, v97
	v_add_f32_e32 v97, v161, v166
	v_add_f32_e32 v161, v167, v168
	v_add_f32_e32 v166, v169, v170
	v_add_f32_e32 v96, v96, v97
	v_add_f32_e32 v97, v161, v166
	v_add_f32_e32 v96, v96, v97
	ds_bpermute_b32 v97, v177, v96
	s_waitcnt lgkmcnt(0)
	v_add_f32_e32 v96, v96, v97
	ds_bpermute_b32 v97, v178, v96
	s_and_saveexec_b64 s[4:5], vcc
	s_cbranch_execz .LBB0_1221
	s_waitcnt lgkmcnt(0)
	v_add_f32_e32 v96, v96, v97
	ds_write_b32 v113, v96 offset:256
;     __device__ __forceinline__ void operator()(f32x4 (&acc)[2][2][4][2], const Unit& u, int wr, int wc, int fr, int fq, LAS unsigned char* lds) const {
;     ...
;             for (int ai = 0; ai < 2; ++ai)
; #pragma unroll
;                 for (int m = 0; m < 4; ++m) { int rr_ = row0 + ai * HALF + m * 16; asm volatile("" : "+v"(rr_)); const float* xr = xp + (size_t)rr_ * DM + col0;
;                     float sq = 0.f;
; #pragma unroll
;                     for (int bj = 0; bj < 2; ++bj) { const f32x4 v0 = *(const f32x4*)(xr + bj * HALF) + gv[bj][0] * acc[ai][bj][m][0], v1 = *(const f32x4*)(xr + bj * HALF + 4) + gv[bj][1] * acc[ai][bj][m][1];
;                         acc[ai][bj][m][0] = v0; acc[ai][bj][m][1] = v1;
;                         sq += ((v0[0] * v0[0] + v0[1] * v0[1]) + (v0[2] * v0[2] + v0[3] * v0[3])) + ((v1[0] * v1[0] + v1[1] * v1[1]) + (v1[2] * v1[2] + v1[3] * v1[3])); }
;                     sq += __shfl_xor(sq, 16); sq += __shfl_xor(sq, 32);
;                     if (fq == 0) P[(ai * HALF + wr * 64 + m * 16 + fr) * 4 + wc] = sq; }
.LBB0_1221:
	s_or_b64 exec, exec, s[4:5]
	v_or_b32_e32 v96, 32, v158
	v_mov_b32_e32 v166, v96
	s_nop 0
	v_ashrrev_i32_e32 v167, 31, v166
	v_lshlrev_b64 v[166:167], 12, v[166:167]
	v_lshl_add_u64 v[166:167], s[36:37], 0, v[166:167]
	v_lshl_add_u64 v[174:175], v[166:167], 0, v[152:153]
	v_add_u32_e32 v250, 48, v158
	v_ashrrev_i32_e32 v251, 31, v250
	v_lshlrev_b64 v[250:251], 12, v[250:251]
	v_lshl_add_u64 v[250:251], s[36:37], 0, v[250:251]
	v_lshl_add_u64 v[250:251], v[250:251], 0, v[152:153]
	global_load_dwordx4 v[234:237], v[250:251], off
	global_load_dwordx4 v[238:241], v[250:251], off offset:16
	global_load_dwordx4 v[242:245], v[250:251], off offset:512
	global_load_dwordx4 v[246:249], v[250:251], off offset:528
	s_waitcnt vmcnt(4)
	v_pk_fma_f32 v[94:95], v[94:95], v[134:135], v[220:221]
	v_pk_fma_f32 v[166:167], v[92:93], v[132:133], v[218:219]
	v_pk_fma_f32 v[90:91], v[90:91], v[130:131], v[224:225]
	v_pk_fma_f32 v[92:93], v[88:89], v[128:129], v[222:223]
	v_pk_fma_f32 v[86:87], v[86:87], v[126:127], v[228:229]
	v_pk_fma_f32 v[88:89], v[84:85], v[124:125], v[226:227]
	v_pk_fma_f32 v[82:83], v[82:83], v[118:119], v[232:233]
	v_pk_fma_f32 v[84:85], v[80:81], v[116:117], v[230:231]
	v_mul_f32_e32 v80, v167, v167
	v_mul_f32_e32 v81, v95, v95
	s_waitcnt lgkmcnt(0)
	v_mul_f32_e32 v97, v93, v93
	v_mul_f32_e32 v161, v91, v91
	v_mul_f32_e32 v168, v89, v89
	v_mul_f32_e32 v169, v87, v87
	v_mul_f32_e32 v170, v85, v85
	v_mul_f32_e32 v171, v83, v83
	v_fmac_f32_e32 v80, v166, v166
	v_fmac_f32_e32 v81, v94, v94
	v_fmac_f32_e32 v97, v92, v92
	v_fmac_f32_e32 v161, v90, v90
	v_fmac_f32_e32 v168, v88, v88
	v_fmac_f32_e32 v169, v86, v86
	v_fmac_f32_e32 v170, v84, v84
	v_fmac_f32_e32 v171, v82, v82
	v_add_f32_e32 v80, v80, v81
	v_add_f32_e32 v81, v97, v161
	v_add_f32_e32 v97, v168, v169
	v_add_f32_e32 v161, v170, v171
	v_add_f32_e32 v80, v80, v81
	v_add_f32_e32 v81, v97, v161
	v_add_f32_e32 v80, v80, v81
	ds_bpermute_b32 v81, v177, v80
	s_waitcnt lgkmcnt(0)
	v_add_f32_e32 v80, v80, v81
	ds_bpermute_b32 v81, v178, v80
	s_and_saveexec_b64 s[4:5], vcc
	s_cbranch_execz .LBB0_1223
	s_waitcnt lgkmcnt(0)
	v_add_f32_e32 v80, v80, v81
	ds_write_b32 v113, v80 offset:512
.LBB0_1223:
	s_or_b64 exec, exec, s[4:5]
	v_or_b32_e32 v80, 48, v158
	v_mov_b32_e32 v168, v80
	s_nop 0
	v_ashrrev_i32_e32 v169, 31, v168
	v_lshlrev_b64 v[168:169], 12, v[168:169]
	v_lshl_add_u64 v[168:169], s[36:37], 0, v[168:169]
	v_lshl_add_u64 v[190:191], v[168:169], 0, v[152:153]
	v_add_u32_e32 v250, 128, v158
	v_ashrrev_i32_e32 v251, 31, v250
	v_lshlrev_b64 v[250:251], 12, v[250:251]
	v_lshl_add_u64 v[250:251], s[36:37], 0, v[250:251]
	v_lshl_add_u64 v[250:251], v[250:251], 0, v[152:153]
	global_load_dwordx4 v[218:221], v[250:251], off
	global_load_dwordx4 v[222:225], v[250:251], off offset:16
	global_load_dwordx4 v[226:229], v[250:251], off offset:512
	global_load_dwordx4 v[230:233], v[250:251], off offset:528
	s_nop 0
	s_waitcnt vmcnt(4)
	v_pk_fma_f32 v[78:79], v[78:79], v[134:135], v[236:237]
	v_pk_fma_f32 v[76:77], v[76:77], v[132:133], v[234:235]
	v_pk_fma_f32 v[74:75], v[74:75], v[130:131], v[240:241]
	v_pk_fma_f32 v[72:73], v[72:73], v[128:129], v[238:239]
	v_pk_fma_f32 v[70:71], v[70:71], v[126:127], v[244:245]
	v_pk_fma_f32 v[68:69], v[68:69], v[124:125], v[242:243]
	v_pk_fma_f32 v[66:67], v[66:67], v[118:119], v[248:249]
	v_pk_fma_f32 v[64:65], v[64:65], v[116:117], v[246:247]
	s_waitcnt lgkmcnt(0)
	v_mul_f32_e32 v81, v77, v77
	v_mul_f32_e32 v97, v79, v79
	v_mul_f32_e32 v161, v73, v73
	v_mul_f32_e32 v168, v75, v75
	v_mul_f32_e32 v169, v69, v69
	v_mul_f32_e32 v170, v71, v71
	v_mul_f32_e32 v171, v65, v65
	v_mul_f32_e32 v172, v67, v67
	v_fmac_f32_e32 v81, v76, v76
	v_fmac_f32_e32 v97, v78, v78
	v_fmac_f32_e32 v161, v72, v72
	v_fmac_f32_e32 v168, v74, v74
	v_fmac_f32_e32 v169, v68, v68
	v_fmac_f32_e32 v170, v70, v70
	v_fmac_f32_e32 v171, v64, v64
	v_fmac_f32_e32 v172, v66, v66
	v_add_f32_e32 v81, v81, v97
	v_add_f32_e32 v97, v161, v168
	v_add_f32_e32 v161, v169, v170
	v_add_f32_e32 v168, v171, v172
	v_add_f32_e32 v81, v81, v97
	v_add_f32_e32 v97, v161, v168
	v_add_f32_e32 v81, v81, v97
	ds_bpermute_b32 v97, v177, v81
	s_waitcnt lgkmcnt(0)
	v_add_f32_e32 v81, v81, v97
	ds_bpermute_b32 v97, v178, v81
	s_and_saveexec_b64 s[4:5], vcc
	s_cbranch_execz .LBB0_1225
	s_waitcnt lgkmcnt(0)
	v_add_f32_e32 v81, v81, v97
	ds_write_b32 v113, v81 offset:768
.LBB0_1225:
	s_or_b64 exec, exec, s[4:5]
	v_add_u32_e32 v168, 0x80, v158
	v_mov_b32_e32 v170, v168
	s_nop 0
	v_ashrrev_i32_e32 v171, 31, v170
	v_lshlrev_b64 v[170:171], 12, v[170:171]
	v_lshl_add_u64 v[170:171], s[36:37], 0, v[170:171]
	v_lshl_add_u64 v[174:175], v[170:171], 0, v[152:153]
	v_add_u32_e32 v250, 144, v158
	v_ashrrev_i32_e32 v251, 31, v250
	v_lshlrev_b64 v[250:251], 12, v[250:251]
	v_lshl_add_u64 v[250:251], s[36:37], 0, v[250:251]
	v_lshl_add_u64 v[250:251], v[250:251], 0, v[152:153]
	global_load_dwordx4 v[234:237], v[250:251], off
	global_load_dwordx4 v[238:241], v[250:251], off offset:16
	global_load_dwordx4 v[242:245], v[250:251], off offset:512
	global_load_dwordx4 v[246:249], v[250:251], off offset:528
	s_waitcnt vmcnt(4)
	v_pk_fma_f32 v[62:63], v[62:63], v[134:135], v[220:221]
	v_pk_fma_f32 v[60:61], v[60:61], v[132:133], v[218:219]
	v_pk_fma_f32 v[58:59], v[58:59], v[130:131], v[224:225]
	v_pk_fma_f32 v[56:57], v[56:57], v[128:129], v[222:223]
	v_pk_fma_f32 v[54:55], v[54:55], v[126:127], v[228:229]
	v_pk_fma_f32 v[52:53], v[52:53], v[124:125], v[226:227]
	v_pk_fma_f32 v[50:51], v[50:51], v[118:119], v[232:233]
	v_pk_fma_f32 v[48:49], v[48:49], v[116:117], v[230:231]
	v_mul_f32_e32 v81, v61, v61
	s_waitcnt lgkmcnt(0)
	v_mul_f32_e32 v97, v63, v63
	v_mul_f32_e32 v161, v57, v57
	v_mul_f32_e32 v169, v59, v59
	v_mul_f32_e32 v170, v53, v53
	v_mul_f32_e32 v171, v55, v55
	v_mul_f32_e32 v172, v49, v49
	v_mul_f32_e32 v173, v51, v51
	v_fmac_f32_e32 v81, v60, v60
	v_fmac_f32_e32 v97, v62, v62
	v_fmac_f32_e32 v161, v56, v56
	v_fmac_f32_e32 v169, v58, v58
	v_fmac_f32_e32 v170, v52, v52
	v_fmac_f32_e32 v171, v54, v54
	v_fmac_f32_e32 v172, v48, v48
	v_fmac_f32_e32 v173, v50, v50
	v_add_f32_e32 v81, v81, v97
	v_add_f32_e32 v97, v161, v169
	v_add_f32_e32 v161, v170, v171
	v_add_f32_e32 v169, v172, v173
	v_add_f32_e32 v81, v81, v97
	v_add_f32_e32 v97, v161, v169
	v_add_f32_e32 v81, v81, v97
	ds_bpermute_b32 v97, v177, v81
	s_waitcnt lgkmcnt(0)
	v_add_f32_e32 v81, v81, v97
	ds_bpermute_b32 v97, v178, v81
	s_and_saveexec_b64 s[4:5], vcc
	s_cbranch_execz .LBB0_1227
	s_waitcnt lgkmcnt(0)
	v_add_f32_e32 v81, v81, v97
	ds_write_b32 v113, v81 offset:2048
;     __device__ __forceinline__ void operator()(f32x4 (&acc)[2][2][4][2], const Unit& u, int wr, int wc, int fr, int fq, LAS unsigned char* lds) const {
;     ...
;             for (int ai = 0; ai < 2; ++ai)
; #pragma unroll
;                 for (int m = 0; m < 4; ++m) { int rr_ = row0 + ai * HALF + m * 16; asm volatile("" : "+v"(rr_)); const float* xr = xp + (size_t)rr_ * DM + col0;
;                     float sq = 0.f;
; #pragma unroll
;                     for (int bj = 0; bj < 2; ++bj) { const f32x4 v0 = *(const f32x4*)(xr + bj * HALF) + gv[bj][0] * acc[ai][bj][m][0], v1 = *(const f32x4*)(xr + bj * HALF + 4) + gv[bj][1] * acc[ai][bj][m][1];
;                         acc[ai][bj][m][0] = v0; acc[ai][bj][m][1] = v1;
;                         sq += ((v0[0] * v0[0] + v0[1] * v0[1]) + (v0[2] * v0[2] + v0[3] * v0[3])) + ((v1[0] * v1[0] + v1[1] * v1[1]) + (v1[2] * v1[2] + v1[3] * v1[3])); }
;                     sq += __shfl_xor(sq, 16); sq += __shfl_xor(sq, 32);
;                     if (fq == 0) P[(ai * HALF + wr * 64 + m * 16 + fr) * 4 + wc] = sq; }
.LBB0_1227:
	s_or_b64 exec, exec, s[4:5]
	v_add_u32_e32 v170, 0x90, v158
	v_mov_b32_e32 v172, v170
	s_nop 0
	v_ashrrev_i32_e32 v173, 31, v172
	v_lshlrev_b64 v[172:173], 12, v[172:173]
	v_lshl_add_u64 v[172:173], s[36:37], 0, v[172:173]
	v_lshl_add_u64 v[194:195], v[172:173], 0, v[152:153]
	v_add_u32_e32 v250, 160, v158
	v_ashrrev_i32_e32 v251, 31, v250
	v_lshlrev_b64 v[250:251], 12, v[250:251]
	v_lshl_add_u64 v[250:251], s[36:37], 0, v[250:251]
	v_lshl_add_u64 v[250:251], v[250:251], 0, v[152:153]
	global_load_dwordx4 v[218:221], v[250:251], off
	global_load_dwordx4 v[222:225], v[250:251], off offset:16
	global_load_dwordx4 v[226:229], v[250:251], off offset:512
	global_load_dwordx4 v[230:233], v[250:251], off offset:528
	s_nop 0
	s_waitcnt vmcnt(4)
	v_pk_fma_f32 v[46:47], v[46:47], v[134:135], v[236:237]
	v_pk_fma_f32 v[44:45], v[44:45], v[132:133], v[234:235]
	v_pk_fma_f32 v[42:43], v[42:43], v[130:131], v[240:241]
	v_pk_fma_f32 v[40:41], v[40:41], v[128:129], v[238:239]
	v_pk_fma_f32 v[38:39], v[38:39], v[126:127], v[244:245]
	v_pk_fma_f32 v[36:37], v[36:37], v[124:125], v[242:243]
	v_pk_fma_f32 v[34:35], v[34:35], v[118:119], v[248:249]
	v_pk_fma_f32 v[32:33], v[32:33], v[116:117], v[246:247]
	v_mul_f32_e32 v81, v45, v45
	s_waitcnt lgkmcnt(0)
	v_mul_f32_e32 v97, v47, v47
	v_mul_f32_e32 v161, v41, v41
	v_mul_f32_e32 v169, v43, v43
	v_mul_f32_e32 v171, v37, v37
	v_mul_f32_e32 v172, v39, v39
	v_mul_f32_e32 v173, v33, v33
	v_mul_f32_e32 v174, v35, v35
	v_fmac_f32_e32 v81, v44, v44
	v_fmac_f32_e32 v97, v46, v46
	v_fmac_f32_e32 v161, v40, v40
	v_fmac_f32_e32 v169, v42, v42
	v_fmac_f32_e32 v171, v36, v36
	v_fmac_f32_e32 v172, v38, v38
	v_fmac_f32_e32 v173, v32, v32
	v_fmac_f32_e32 v174, v34, v34
	v_add_f32_e32 v81, v81, v97
	v_add_f32_e32 v97, v161, v169
	v_add_f32_e32 v161, v171, v172
	v_add_f32_e32 v169, v173, v174
	v_add_f32_e32 v81, v81, v97
	v_add_f32_e32 v97, v161, v169
	v_add_f32_e32 v81, v81, v97
	ds_bpermute_b32 v97, v177, v81
	s_waitcnt lgkmcnt(0)
	v_add_f32_e32 v81, v81, v97
	ds_bpermute_b32 v97, v178, v81
	s_and_saveexec_b64 s[4:5], vcc
	s_cbranch_execz .LBB0_1229
	s_waitcnt lgkmcnt(0)
	v_add_f32_e32 v81, v81, v97
	ds_write_b32 v113, v81 offset:2304
.LBB0_1229:
	s_or_b64 exec, exec, s[4:5]
	v_add_u32_e32 v172, 0xa0, v158
	v_mov_b32_e32 v174, v172
	s_nop 0
	v_ashrrev_i32_e32 v175, 31, v174
	v_lshlrev_b64 v[174:175], 12, v[174:175]
	v_lshl_add_u64 v[174:175], s[36:37], 0, v[174:175]
	v_lshl_add_u64 v[174:175], v[174:175], 0, v[152:153]
	v_add_u32_e32 v250, 176, v158
	v_ashrrev_i32_e32 v251, 31, v250
	v_lshlrev_b64 v[250:251], 12, v[250:251]
	v_lshl_add_u64 v[250:251], s[36:37], 0, v[250:251]
	v_lshl_add_u64 v[250:251], v[250:251], 0, v[152:153]
	global_load_dwordx4 v[234:237], v[250:251], off
	global_load_dwordx4 v[238:241], v[250:251], off offset:16
	global_load_dwordx4 v[242:245], v[250:251], off offset:512
	global_load_dwordx4 v[246:249], v[250:251], off offset:528
	s_waitcnt vmcnt(4)
	v_pk_fma_f32 v[30:31], v[30:31], v[134:135], v[220:221]
	v_pk_fma_f32 v[28:29], v[28:29], v[132:133], v[218:219]
	v_pk_fma_f32 v[26:27], v[26:27], v[130:131], v[224:225]
	v_pk_fma_f32 v[24:25], v[24:25], v[128:129], v[222:223]
	v_pk_fma_f32 v[22:23], v[22:23], v[126:127], v[228:229]
	v_pk_fma_f32 v[20:21], v[20:21], v[124:125], v[226:227]
	v_pk_fma_f32 v[18:19], v[18:19], v[118:119], v[232:233]
	v_pk_fma_f32 v[16:17], v[16:17], v[116:117], v[230:231]
	v_mul_f32_e32 v81, v29, v29
	s_waitcnt lgkmcnt(0)
	v_mul_f32_e32 v97, v31, v31
	v_mul_f32_e32 v161, v25, v25
	v_mul_f32_e32 v169, v27, v27
	v_mul_f32_e32 v171, v21, v21
	v_mul_f32_e32 v173, v23, v23
	v_mul_f32_e32 v174, v17, v17
	v_mul_f32_e32 v175, v19, v19
	v_fmac_f32_e32 v81, v28, v28
	v_fmac_f32_e32 v97, v30, v30
	v_fmac_f32_e32 v161, v24, v24
	v_fmac_f32_e32 v169, v26, v26
	v_fmac_f32_e32 v171, v20, v20
	v_fmac_f32_e32 v173, v22, v22
	v_fmac_f32_e32 v174, v16, v16
	v_fmac_f32_e32 v175, v18, v18
	v_add_f32_e32 v81, v81, v97
	v_add_f32_e32 v97, v161, v169
	v_add_f32_e32 v161, v171, v173
	v_add_f32_e32 v169, v174, v175
	v_add_f32_e32 v81, v81, v97
	v_add_f32_e32 v97, v161, v169
	v_add_f32_e32 v81, v81, v97
	ds_bpermute_b32 v97, v177, v81
	s_waitcnt lgkmcnt(0)
	v_add_f32_e32 v81, v81, v97
	ds_bpermute_b32 v97, v178, v81
	s_and_saveexec_b64 s[4:5], vcc
	s_cbranch_execz .LBB0_1231
	s_waitcnt lgkmcnt(0)
	v_add_f32_e32 v81, v81, v97
	ds_write_b32 v113, v81 offset:2560
.LBB0_1231:
	s_or_b64 exec, exec, s[4:5]
	v_add_u32_e32 v174, 0xb0, v158
	v_mov_b32_e32 v186, v174
	s_nop 0
	v_ashrrev_i32_e32 v187, 31, v186
	v_lshlrev_b64 v[186:187], 12, v[186:187]
	v_lshl_add_u64 v[186:187], s[36:37], 0, v[186:187]
	v_lshl_add_u64 v[198:199], v[186:187], 0, v[152:153]
	s_nop 0
	s_waitcnt vmcnt(3)
	v_pk_fma_f32 v[134:135], v[14:15], v[134:135], v[236:237]
	v_pk_fma_f32 v[132:133], v[12:13], v[132:133], v[234:235]
	s_waitcnt vmcnt(2)
	v_pk_fma_f32 v[130:131], v[10:11], v[130:131], v[240:241]
	v_pk_fma_f32 v[128:129], v[8:9], v[128:129], v[238:239]
	s_waitcnt vmcnt(1)
	v_pk_fma_f32 v[126:127], v[6:7], v[126:127], v[244:245]
	v_pk_fma_f32 v[124:125], v[4:5], v[124:125], v[242:243]
	s_waitcnt vmcnt(0)
	v_pk_fma_f32 v[118:119], v[2:3], v[118:119], v[248:249]
	v_pk_fma_f32 v[116:117], v[0:1], v[116:117], v[246:247]
	v_mul_f32_e32 v0, v133, v133
	v_mul_f32_e32 v1, v135, v135
	v_mul_f32_e32 v2, v129, v129
	v_mul_f32_e32 v3, v131, v131
	v_mul_f32_e32 v4, v125, v125
	v_mul_f32_e32 v5, v127, v127
	v_mul_f32_e32 v6, v117, v117
	v_mul_f32_e32 v7, v119, v119
	v_fmac_f32_e32 v0, v132, v132
	v_fmac_f32_e32 v1, v134, v134
	v_fmac_f32_e32 v2, v128, v128
	v_fmac_f32_e32 v3, v130, v130
	v_fmac_f32_e32 v4, v124, v124
	v_fmac_f32_e32 v5, v126, v126
	v_fmac_f32_e32 v6, v116, v116
	v_fmac_f32_e32 v7, v118, v118
	v_add_f32_e32 v0, v0, v1
	v_add_f32_e32 v1, v2, v3
	v_add_f32_e32 v2, v4, v5
	v_add_f32_e32 v3, v6, v7
	v_add_f32_e32 v0, v0, v1
	v_add_f32_e32 v1, v2, v3
	v_add_f32_e32 v0, v0, v1
	ds_bpermute_b32 v1, v177, v0
	s_waitcnt lgkmcnt(0)
	v_add_f32_e32 v0, v0, v1
	ds_bpermute_b32 v1, v178, v0
	s_and_saveexec_b64 s[4:5], vcc
	s_cbranch_execz .LBB0_1233
	s_waitcnt lgkmcnt(0)
	v_add_f32_e32 v0, v0, v1
	ds_write_b32 v113, v0 offset:2816
